# attnA: workgroup barrier after each unit removed (all per-unit state is wave-private; pass 2 keeps its own barrier)
# baseline (speedup 1.0000x reference)
; __device__ __forceinline__ void run_phase(const Args& a0, int ph, LAS unsigned char* lds) {
;     ...
;             for (int k = 0; k < 3; ++k) attnC_unit(a, 96 * (c & 7) + 32 * k + (c >> 3), lds);
;             __syncthreads();
;             for (int k = 0; k < 3; ++k) { attnA_unit(a, 96 * (c & 7) + 32 * k + (c >> 3), lds); __syncthreads(); }
.LBB0_260:
	v_readlane_b32 s0, v255, 36
	s_add_i32 s0, s0, 1
	v_readlane_b32 s26, v255, 34
	s_cmp_eq_u32 s0, 3
	v_readlane_b32 s17, v255, 33
	v_readlane_b32 s27, v255, 35
	s_cbranch_scc1 .LBB0_284
